# late-weight transposes in P1 spread over all 256 CUs instead of last 60; vmcnt(0) hoisted out of P1 K-loop
# speedup vs baseline: 1.0236x; 1.0236x over previous
.LBB0_150:
	s_ashr_i32 s47, s46, 31
	s_lshl_b64 s[8:9], s[46:47], 19
	s_add_u32 s50, s43, s8
	s_addc_u32 s51, s68, s9
	s_and_b64 s[8:9], s[48:49], exec
	s_cselect_b32 s3, s51, s1
	s_cselect_b32 s33, s50, s0
	s_ashr_i32 s45, s44, 31
	s_lshl_b64 s[8:9], s[44:45], 19
	s_add_u32 s52, s69, s8
	s_addc_u32 s53, s70, s9
	s_and_b64 s[8:9], s[48:49], exec
	s_cselect_b32 s45, s53, s7
	s_cselect_b32 s47, s52, s6
	s_add_u32 s0, s0, 0x40080
	s_addc_u32 s1, s1, 0
	s_add_u32 s56, s6, 0x100
	v_mov_b32_e32 v2, 0
	s_addc_u32 s57, s7, 0
	s_mov_b32 s58, -2
	s_waitcnt lgkmcnt(0)
	v_mov_b32_e32 v3, v2
	v_mov_b32_e32 v4, v2
	v_mov_b32_e32 v5, v2
	v_mov_b32_e32 v6, v2
	v_mov_b32_e32 v7, v2
	v_mov_b32_e32 v8, v2
	v_mov_b32_e32 v9, v2
	v_mov_b32_e32 v18, v2
	v_mov_b32_e32 v19, v2
	v_mov_b32_e32 v20, v2
	v_mov_b32_e32 v21, v2
	v_mov_b32_e32 v22, v2
	v_mov_b32_e32 v23, v2
	v_mov_b32_e32 v24, v2
	v_mov_b32_e32 v25, v2
	v_mov_b32_e32 v34, v2
	v_mov_b32_e32 v35, v2
	v_mov_b32_e32 v36, v2
	v_mov_b32_e32 v37, v2
	v_mov_b32_e32 v38, v2
	v_mov_b32_e32 v39, v2
	v_mov_b32_e32 v40, v2
	v_mov_b32_e32 v41, v2
	v_mov_b32_e32 v50, v2
	v_mov_b32_e32 v51, v2
	v_mov_b32_e32 v52, v2
	v_mov_b32_e32 v53, v2
	v_mov_b32_e32 v54, v2
	v_mov_b32_e32 v55, v2
	v_mov_b32_e32 v56, v2
	v_mov_b32_e32 v57, v2
	v_mov_b32_e32 v10, v2
	v_mov_b32_e32 v11, v2
	v_mov_b32_e32 v12, v2
	v_mov_b32_e32 v13, v2
	v_mov_b32_e32 v14, v2
	v_mov_b32_e32 v15, v2
	v_mov_b32_e32 v16, v2
	v_mov_b32_e32 v17, v2
	v_mov_b32_e32 v26, v2
	v_mov_b32_e32 v27, v2
	v_mov_b32_e32 v28, v2
	v_mov_b32_e32 v29, v2
	v_mov_b32_e32 v30, v2
	v_mov_b32_e32 v31, v2
	v_mov_b32_e32 v32, v2
	v_mov_b32_e32 v33, v2
	v_mov_b32_e32 v42, v2
	v_mov_b32_e32 v43, v2
	v_mov_b32_e32 v44, v2
	v_mov_b32_e32 v45, v2
	v_mov_b32_e32 v46, v2
	v_mov_b32_e32 v47, v2
	v_mov_b32_e32 v48, v2
	v_mov_b32_e32 v49, v2
	v_mov_b32_e32 v58, v2
	v_mov_b32_e32 v59, v2
	v_mov_b32_e32 v60, v2
	v_mov_b32_e32 v61, v2
	v_mov_b32_e32 v62, v2
	v_mov_b32_e32 v63, v2
	v_mov_b32_e32 v64, v2
	v_mov_b32_e32 v65, v2
	v_mov_b32_e32 v66, v2
	v_mov_b32_e32 v67, v2
	v_mov_b32_e32 v68, v2
	v_mov_b32_e32 v69, v2
	v_mov_b32_e32 v70, v2
	v_mov_b32_e32 v71, v2
	v_mov_b32_e32 v72, v2
	v_mov_b32_e32 v73, v2
	v_mov_b32_e32 v82, v2
	v_mov_b32_e32 v83, v2
	v_mov_b32_e32 v84, v2
	v_mov_b32_e32 v85, v2
	v_mov_b32_e32 v86, v2
	v_mov_b32_e32 v87, v2
	v_mov_b32_e32 v88, v2
	v_mov_b32_e32 v89, v2
	v_mov_b32_e32 v98, v2
	v_mov_b32_e32 v99, v2
	v_mov_b32_e32 v100, v2
	v_mov_b32_e32 v101, v2
	v_mov_b32_e32 v102, v2
	v_mov_b32_e32 v103, v2
	v_mov_b32_e32 v104, v2
	v_mov_b32_e32 v105, v2
	v_mov_b32_e32 v114, v2
	v_mov_b32_e32 v115, v2
	v_mov_b32_e32 v116, v2
	v_mov_b32_e32 v117, v2
	v_mov_b32_e32 v118, v2
	v_mov_b32_e32 v119, v2
	v_mov_b32_e32 v120, v2
	v_mov_b32_e32 v121, v2
	v_mov_b32_e32 v74, v2
	v_mov_b32_e32 v75, v2
	v_mov_b32_e32 v76, v2
	v_mov_b32_e32 v77, v2
	v_mov_b32_e32 v78, v2
	v_mov_b32_e32 v79, v2
	v_mov_b32_e32 v80, v2
	v_mov_b32_e32 v81, v2
	v_mov_b32_e32 v90, v2
	v_mov_b32_e32 v91, v2
	v_mov_b32_e32 v92, v2
	v_mov_b32_e32 v93, v2
	v_mov_b32_e32 v94, v2
	v_mov_b32_e32 v95, v2
	v_mov_b32_e32 v96, v2
	v_mov_b32_e32 v97, v2
	v_mov_b32_e32 v106, v2
	v_mov_b32_e32 v107, v2
	v_mov_b32_e32 v108, v2
	v_mov_b32_e32 v109, v2
	v_mov_b32_e32 v110, v2
	v_mov_b32_e32 v111, v2
	v_mov_b32_e32 v112, v2
	v_mov_b32_e32 v113, v2
	v_mov_b32_e32 v122, v2
	v_mov_b32_e32 v123, v2
	v_mov_b32_e32 v124, v2
	v_mov_b32_e32 v125, v2
	v_mov_b32_e32 v126, v2
	v_mov_b32_e32 v127, v2
	v_mov_b32_e32 v128, v2
	v_mov_b32_e32 v129, v2
	s_waitcnt vmcnt(0)
.LBB0_151:
	ds_read_b128 v[130:133], v223
	ds_read_b128 v[134:137], v223 offset:1024
	ds_read_b128 v[156:159], v223 offset:2048
	ds_read_b128 v[160:163], v223 offset:3072
	ds_read_b128 v[164:167], v224
	ds_read_b128 v[168:171], v224 offset:1024
	ds_read_b128 v[172:175], v224 offset:2048
	ds_read_b128 v[186:189], v224 offset:3072
	s_add_u32 s6, s0, 0xfffc0080
	s_addc_u32 s7, s1, -1
	s_cmp_eq_u32 s58, 12
	s_cselect_b32 s9, s3, s7
	s_cselect_b32 s8, s33, s6
	s_cselect_b32 s7, s45, s57
	s_cselect_b32 s6, s47, s56
	v_lshl_add_u64 v[178:179], s[0:1], 0, v[150:151]
	s_add_i32 m0, s55, 0xc000
	ds_read_b128 v[190:193], v225
	ds_read_b128 v[194:197], v225 offset:1024
	ds_read_b128 v[198:201], v225 offset:2048
	ds_read_b128 v[202:205], v225 offset:3072
	ds_read_b128 v[206:209], v225 offset:4096
	ds_read_b128 v[210:213], v225 offset:5120
	ds_read_b128 v[214:217], v225 offset:6144
	ds_read_b128 v[218:221], v225 offset:7168
	global_load_lds_dwordx4 v[178:179], off
	v_lshl_add_u64 v[178:179], s[0:1], 0, v[152:153]
	s_add_i32 m0, s55, 0xe000
	s_nop 0
	global_load_lds_dwordx4 v[178:179], off
	s_waitcnt vmcnt(8)
	s_waitcnt lgkmcnt(0)
	s_barrier
	s_setprio 1
	s_waitcnt lgkmcnt(0)
	v_mfma_f32_16x16x32_bf16 v[126:129], v[130:133], v[190:193], v[126:129]
	v_mfma_f32_16x16x32_bf16 v[122:125], v[156:159], v[190:193], v[122:125]
	v_mfma_f32_16x16x32_bf16 v[110:113], v[130:133], v[198:201], v[110:113]
	v_mfma_f32_16x16x32_bf16 v[106:109], v[156:159], v[198:201], v[106:109]
	v_mfma_f32_16x16x32_bf16 v[94:97], v[130:133], v[206:209], v[94:97]
	v_mfma_f32_16x16x32_bf16 v[90:93], v[156:159], v[206:209], v[90:93]
	v_mfma_f32_16x16x32_bf16 v[78:81], v[130:133], v[214:217], v[78:81]
	v_mfma_f32_16x16x32_bf16 v[74:77], v[156:159], v[214:217], v[74:77]
	v_mfma_f32_16x16x32_bf16 v[126:129], v[134:137], v[194:197], v[126:129]
	v_mfma_f32_16x16x32_bf16 v[122:125], v[160:163], v[194:197], v[122:125]
	v_mfma_f32_16x16x32_bf16 v[110:113], v[134:137], v[202:205], v[110:113]
	v_mfma_f32_16x16x32_bf16 v[106:109], v[160:163], v[202:205], v[106:109]
	v_mfma_f32_16x16x32_bf16 v[94:97], v[134:137], v[210:213], v[94:97]
	v_mfma_f32_16x16x32_bf16 v[90:93], v[160:163], v[210:213], v[90:93]
	v_mfma_f32_16x16x32_bf16 v[78:81], v[134:137], v[218:221], v[78:81]
	v_mfma_f32_16x16x32_bf16 v[74:77], v[160:163], v[218:221], v[74:77]
	s_setprio 0
	s_setprio 1
	v_mfma_f32_16x16x32_bf16 v[118:121], v[164:167], v[190:193], v[118:121]
	v_mfma_f32_16x16x32_bf16 v[114:117], v[172:175], v[190:193], v[114:117]
	v_mfma_f32_16x16x32_bf16 v[102:105], v[164:167], v[198:201], v[102:105]
	v_mfma_f32_16x16x32_bf16 v[98:101], v[172:175], v[198:201], v[98:101]
	v_mfma_f32_16x16x32_bf16 v[86:89], v[164:167], v[206:209], v[86:89]
	v_mfma_f32_16x16x32_bf16 v[82:85], v[172:175], v[206:209], v[82:85]
	v_mfma_f32_16x16x32_bf16 v[70:73], v[164:167], v[214:217], v[70:73]
	v_mfma_f32_16x16x32_bf16 v[66:69], v[172:175], v[214:217], v[66:69]
	v_mfma_f32_16x16x32_bf16 v[118:121], v[168:171], v[194:197], v[118:121]
	v_mfma_f32_16x16x32_bf16 v[114:117], v[186:189], v[194:197], v[114:117]
	v_mfma_f32_16x16x32_bf16 v[102:105], v[168:171], v[202:205], v[102:105]
	v_mfma_f32_16x16x32_bf16 v[98:101], v[186:189], v[202:205], v[98:101]
	v_mfma_f32_16x16x32_bf16 v[86:89], v[168:171], v[210:213], v[86:89]
	v_mfma_f32_16x16x32_bf16 v[82:85], v[186:189], v[210:213], v[82:85]
	v_mfma_f32_16x16x32_bf16 v[70:73], v[168:171], v[218:221], v[70:73]
	v_mfma_f32_16x16x32_bf16 v[66:69], v[186:189], v[218:221], v[66:69]
	s_setprio 0
	s_barrier
	s_add_i32 s59, s86, s71
	v_lshl_add_u64 v[178:179], s[6:7], 0, v[140:141]
	s_mov_b32 m0, s59
	ds_read_b128 v[190:193], v225 offset:16384
	ds_read_b128 v[194:197], v225 offset:17408
	ds_read_b128 v[198:201], v225 offset:18432
	ds_read_b128 v[202:205], v225 offset:19456
	ds_read_b128 v[206:209], v225 offset:20480
	ds_read_b128 v[210:213], v225 offset:21504
	ds_read_b128 v[214:217], v225 offset:22528
	ds_read_b128 v[218:221], v225 offset:23552
	global_load_lds_dwordx4 v[178:179], off
	s_add_i32 m0, s59, 0x2000
	s_add_u32 s60, s6, 0x40000
	v_lshl_add_u64 v[182:183], s[6:7], 0, v[144:145]
	s_addc_u32 s61, s7, 0
	s_add_i32 s59, s87, s71
	global_load_lds_dwordx4 v[182:183], off
	v_lshl_add_u64 v[232:233], s[60:61], 0, v[140:141]
	s_mov_b32 m0, s59
	v_lshl_add_u64 v[234:235], s[8:9], 0, v[142:143]
	global_load_lds_dwordx4 v[232:233], off
	v_lshl_add_u64 v[232:233], s[60:61], 0, v[144:145]
	s_add_i32 m0, s59, 0x2000
	s_nop 0
	global_load_lds_dwordx4 v[232:233], off
	v_lshl_add_u64 v[232:233], s[8:9], 0, v[138:139]
	s_mov_b32 m0, s55
	s_nop 0
	global_load_lds_dwordx4 v[232:233], off
	s_mov_b32 m0, s72
	s_nop 0
	global_load_lds_dwordx4 v[234:235], off
	s_waitcnt vmcnt(8)
	s_waitcnt lgkmcnt(0)
	s_barrier
	s_setprio 1
	s_waitcnt lgkmcnt(0)
	v_mfma_f32_16x16x32_bf16 v[62:65], v[130:133], v[190:193], v[62:65]
	v_mfma_f32_16x16x32_bf16 v[58:61], v[156:159], v[190:193], v[58:61]
	v_mfma_f32_16x16x32_bf16 v[46:49], v[130:133], v[198:201], v[46:49]
	v_mfma_f32_16x16x32_bf16 v[42:45], v[156:159], v[198:201], v[42:45]
	v_mfma_f32_16x16x32_bf16 v[30:33], v[130:133], v[206:209], v[30:33]
	v_mfma_f32_16x16x32_bf16 v[26:29], v[156:159], v[206:209], v[26:29]
	v_mfma_f32_16x16x32_bf16 v[14:17], v[130:133], v[214:217], v[14:17]
	v_mfma_f32_16x16x32_bf16 v[10:13], v[156:159], v[214:217], v[10:13]
	v_mfma_f32_16x16x32_bf16 v[62:65], v[134:137], v[194:197], v[62:65]
	v_mfma_f32_16x16x32_bf16 v[58:61], v[160:163], v[194:197], v[58:61]
	v_mfma_f32_16x16x32_bf16 v[46:49], v[134:137], v[202:205], v[46:49]
	v_mfma_f32_16x16x32_bf16 v[42:45], v[160:163], v[202:205], v[42:45]
	v_mfma_f32_16x16x32_bf16 v[30:33], v[134:137], v[210:213], v[30:33]
	v_mfma_f32_16x16x32_bf16 v[26:29], v[160:163], v[210:213], v[26:29]
	v_mfma_f32_16x16x32_bf16 v[14:17], v[134:137], v[218:221], v[14:17]
	v_mfma_f32_16x16x32_bf16 v[10:13], v[160:163], v[218:221], v[10:13]
	s_setprio 0
	s_setprio 1
	v_mfma_f32_16x16x32_bf16 v[54:57], v[164:167], v[190:193], v[54:57]
	v_mfma_f32_16x16x32_bf16 v[50:53], v[172:175], v[190:193], v[50:53]
	v_mfma_f32_16x16x32_bf16 v[38:41], v[164:167], v[198:201], v[38:41]
	v_mfma_f32_16x16x32_bf16 v[34:37], v[172:175], v[198:201], v[34:37]
	v_mfma_f32_16x16x32_bf16 v[22:25], v[164:167], v[206:209], v[22:25]
	v_mfma_f32_16x16x32_bf16 v[18:21], v[172:175], v[206:209], v[18:21]
	v_mfma_f32_16x16x32_bf16 v[6:9], v[164:167], v[214:217], v[6:9]
	v_mfma_f32_16x16x32_bf16 v[2:5], v[172:175], v[214:217], v[2:5]
	v_mfma_f32_16x16x32_bf16 v[54:57], v[168:171], v[194:197], v[54:57]
	v_mfma_f32_16x16x32_bf16 v[50:53], v[186:189], v[194:197], v[50:53]
	v_mfma_f32_16x16x32_bf16 v[38:41], v[168:171], v[202:205], v[38:41]
	v_mfma_f32_16x16x32_bf16 v[34:37], v[186:189], v[202:205], v[34:37]
	v_mfma_f32_16x16x32_bf16 v[22:25], v[168:171], v[210:213], v[22:25]
	v_mfma_f32_16x16x32_bf16 v[18:21], v[186:189], v[210:213], v[18:21]
	v_mfma_f32_16x16x32_bf16 v[6:9], v[168:171], v[218:221], v[6:9]
	v_mfma_f32_16x16x32_bf16 v[2:5], v[186:189], v[218:221], v[2:5]
	s_setprio 0
	s_barrier
	s_add_i32 s59, 0, 0x18000
	s_add_i32 s60, 0, 0x1c000
	v_add_u32_e32 v160, s59, v181
	v_add_u32_e32 v176, s60, v181
	ds_read_b128 v[130:133], v160
	ds_read_b128 v[134:137], v160 offset:1024
	ds_read_b128 v[156:159], v160 offset:2048
	ds_read_b128 v[160:163], v160 offset:3072
	ds_read_b128 v[164:167], v176
	ds_read_b128 v[168:171], v176 offset:1024
	ds_read_b128 v[172:175], v176 offset:2048
	ds_read_b128 v[186:189], v176 offset:3072
	s_add_u32 s8, s8, 0x40000
	s_addc_u32 s9, s9, 0
	s_mov_b32 m0, s73
	v_lshl_add_u64 v[236:237], s[8:9], 0, v[138:139]
	ds_read_b128 v[190:193], v225 offset:32768
	ds_read_b128 v[194:197], v225 offset:33792
	ds_read_b128 v[198:201], v225 offset:34816
	ds_read_b128 v[202:205], v225 offset:35840
	ds_read_b128 v[206:209], v225 offset:36864
	ds_read_b128 v[210:213], v225 offset:37888
	ds_read_b128 v[214:217], v225 offset:38912
	ds_read_b128 v[218:221], v225 offset:39936
	global_load_lds_dwordx4 v[236:237], off
	v_lshl_add_u64 v[236:237], s[8:9], 0, v[142:143]
	s_mov_b32 m0, s74
	s_nop 0
	global_load_lds_dwordx4 v[236:237], off
	s_waitcnt vmcnt(8)
	s_waitcnt lgkmcnt(0)
	s_barrier
	s_setprio 1
	s_waitcnt lgkmcnt(0)
	v_mfma_f32_16x16x32_bf16 v[126:129], v[130:133], v[190:193], v[126:129]
	v_mfma_f32_16x16x32_bf16 v[122:125], v[156:159], v[190:193], v[122:125]
	v_mfma_f32_16x16x32_bf16 v[110:113], v[130:133], v[198:201], v[110:113]
	v_mfma_f32_16x16x32_bf16 v[106:109], v[156:159], v[198:201], v[106:109]
	v_mfma_f32_16x16x32_bf16 v[94:97], v[130:133], v[206:209], v[94:97]
	v_mfma_f32_16x16x32_bf16 v[90:93], v[156:159], v[206:209], v[90:93]
	v_mfma_f32_16x16x32_bf16 v[78:81], v[130:133], v[214:217], v[78:81]
	v_mfma_f32_16x16x32_bf16 v[74:77], v[156:159], v[214:217], v[74:77]
	v_mfma_f32_16x16x32_bf16 v[126:129], v[134:137], v[194:197], v[126:129]
	v_mfma_f32_16x16x32_bf16 v[122:125], v[160:163], v[194:197], v[122:125]
	v_mfma_f32_16x16x32_bf16 v[110:113], v[134:137], v[202:205], v[110:113]
	v_mfma_f32_16x16x32_bf16 v[106:109], v[160:163], v[202:205], v[106:109]
	v_mfma_f32_16x16x32_bf16 v[94:97], v[134:137], v[210:213], v[94:97]
	v_mfma_f32_16x16x32_bf16 v[90:93], v[160:163], v[210:213], v[90:93]
	v_mfma_f32_16x16x32_bf16 v[78:81], v[134:137], v[218:221], v[78:81]
	v_mfma_f32_16x16x32_bf16 v[74:77], v[160:163], v[218:221], v[74:77]
	s_setprio 0
	s_setprio 1
	v_mfma_f32_16x16x32_bf16 v[118:121], v[164:167], v[190:193], v[118:121]
	v_mfma_f32_16x16x32_bf16 v[114:117], v[172:175], v[190:193], v[114:117]
	v_mfma_f32_16x16x32_bf16 v[102:105], v[164:167], v[198:201], v[102:105]
	v_mfma_f32_16x16x32_bf16 v[98:101], v[172:175], v[198:201], v[98:101]
	v_mfma_f32_16x16x32_bf16 v[86:89], v[164:167], v[206:209], v[86:89]
	v_mfma_f32_16x16x32_bf16 v[82:85], v[172:175], v[206:209], v[82:85]
	v_mfma_f32_16x16x32_bf16 v[70:73], v[164:167], v[214:217], v[70:73]
	v_mfma_f32_16x16x32_bf16 v[66:69], v[172:175], v[214:217], v[66:69]
	v_mfma_f32_16x16x32_bf16 v[118:121], v[168:171], v[194:197], v[118:121]
	v_mfma_f32_16x16x32_bf16 v[114:117], v[186:189], v[194:197], v[114:117]
	v_mfma_f32_16x16x32_bf16 v[102:105], v[168:171], v[202:205], v[102:105]
	v_mfma_f32_16x16x32_bf16 v[98:101], v[186:189], v[202:205], v[98:101]
	v_mfma_f32_16x16x32_bf16 v[86:89], v[168:171], v[210:213], v[86:89]
	v_mfma_f32_16x16x32_bf16 v[82:85], v[186:189], v[210:213], v[82:85]
	v_mfma_f32_16x16x32_bf16 v[70:73], v[168:171], v[218:221], v[70:73]
	v_mfma_f32_16x16x32_bf16 v[66:69], v[186:189], v[218:221], v[66:69]
	s_setprio 0
	s_barrier
	s_add_i32 s8, s59, s71
	v_lshl_add_u64 v[178:179], v[178:179], 0, s[38:39]
	s_mov_b32 m0, s8
	ds_read_b128 v[190:193], v225 offset:49152
	ds_read_b128 v[194:197], v225 offset:50176
	ds_read_b128 v[198:201], v225 offset:51200
	ds_read_b128 v[202:205], v225 offset:52224
	ds_read_b128 v[206:209], v225 offset:53248
	ds_read_b128 v[210:213], v225 offset:54272
	ds_read_b128 v[214:217], v225 offset:55296
	ds_read_b128 v[218:221], v225 offset:56320
	global_load_lds_dwordx4 v[178:179], off
	s_add_i32 m0, s8, 0x2000
	s_add_u32 s6, s6, 0x40080
	v_lshl_add_u64 v[178:179], v[182:183], 0, s[38:39]
	s_addc_u32 s7, s7, 0
	s_add_i32 s8, s60, s71
	global_load_lds_dwordx4 v[178:179], off
	v_lshl_add_u64 v[178:179], s[6:7], 0, v[140:141]
	s_mov_b32 m0, s8
	s_nop 0
	global_load_lds_dwordx4 v[178:179], off
	v_lshl_add_u64 v[178:179], s[6:7], 0, v[144:145]
	s_add_i32 m0, s8, 0x2000
	s_nop 0
	global_load_lds_dwordx4 v[178:179], off
	v_lshl_add_u64 v[178:179], v[232:233], 0, s[38:39]
	s_mov_b32 m0, s79
	s_nop 0
	global_load_lds_dwordx4 v[178:179], off
	v_lshl_add_u64 v[178:179], v[234:235], 0, s[38:39]
	s_mov_b32 m0, s80
	s_nop 0
	global_load_lds_dwordx4 v[178:179], off
	s_waitcnt vmcnt(8)
	s_waitcnt lgkmcnt(0)
	s_barrier
	s_setprio 1
	s_waitcnt lgkmcnt(0)
	v_mfma_f32_16x16x32_bf16 v[62:65], v[130:133], v[190:193], v[62:65]
	v_mfma_f32_16x16x32_bf16 v[58:61], v[156:159], v[190:193], v[58:61]
	v_mfma_f32_16x16x32_bf16 v[46:49], v[130:133], v[198:201], v[46:49]
	v_mfma_f32_16x16x32_bf16 v[42:45], v[156:159], v[198:201], v[42:45]
	v_mfma_f32_16x16x32_bf16 v[30:33], v[130:133], v[206:209], v[30:33]
	v_mfma_f32_16x16x32_bf16 v[26:29], v[156:159], v[206:209], v[26:29]
	v_mfma_f32_16x16x32_bf16 v[14:17], v[130:133], v[214:217], v[14:17]
	v_mfma_f32_16x16x32_bf16 v[10:13], v[156:159], v[214:217], v[10:13]
	v_mfma_f32_16x16x32_bf16 v[62:65], v[134:137], v[194:197], v[62:65]
	v_mfma_f32_16x16x32_bf16 v[58:61], v[160:163], v[194:197], v[58:61]
	v_mfma_f32_16x16x32_bf16 v[46:49], v[134:137], v[202:205], v[46:49]
	v_mfma_f32_16x16x32_bf16 v[42:45], v[160:163], v[202:205], v[42:45]
	v_mfma_f32_16x16x32_bf16 v[30:33], v[134:137], v[210:213], v[30:33]
	v_mfma_f32_16x16x32_bf16 v[26:29], v[160:163], v[210:213], v[26:29]
	v_mfma_f32_16x16x32_bf16 v[14:17], v[134:137], v[218:221], v[14:17]
	v_mfma_f32_16x16x32_bf16 v[10:13], v[160:163], v[218:221], v[10:13]
	s_setprio 0
	s_setprio 1
	v_mfma_f32_16x16x32_bf16 v[54:57], v[164:167], v[190:193], v[54:57]
	v_mfma_f32_16x16x32_bf16 v[50:53], v[172:175], v[190:193], v[50:53]
	v_mfma_f32_16x16x32_bf16 v[38:41], v[164:167], v[198:201], v[38:41]
	v_mfma_f32_16x16x32_bf16 v[34:37], v[172:175], v[198:201], v[34:37]
	v_mfma_f32_16x16x32_bf16 v[22:25], v[164:167], v[206:209], v[22:25]
	v_mfma_f32_16x16x32_bf16 v[18:21], v[172:175], v[206:209], v[18:21]
	v_mfma_f32_16x16x32_bf16 v[6:9], v[164:167], v[214:217], v[6:9]
	v_mfma_f32_16x16x32_bf16 v[2:5], v[172:175], v[214:217], v[2:5]
	v_mfma_f32_16x16x32_bf16 v[54:57], v[168:171], v[194:197], v[54:57]
	v_mfma_f32_16x16x32_bf16 v[50:53], v[186:189], v[194:197], v[50:53]
	v_mfma_f32_16x16x32_bf16 v[38:41], v[168:171], v[202:205], v[38:41]
	v_mfma_f32_16x16x32_bf16 v[34:37], v[186:189], v[202:205], v[34:37]
	v_mfma_f32_16x16x32_bf16 v[22:25], v[168:171], v[210:213], v[22:25]
	v_mfma_f32_16x16x32_bf16 v[18:21], v[186:189], v[210:213], v[18:21]
	v_mfma_f32_16x16x32_bf16 v[6:9], v[168:171], v[218:221], v[6:9]
	v_mfma_f32_16x16x32_bf16 v[2:5], v[186:189], v[218:221], v[2:5]
	s_setprio 0
	s_barrier
	s_add_i32 s58, s58, 2
	s_add_u32 s0, s0, 0x100
	s_addc_u32 s1, s1, 0
	s_add_u32 s56, s56, 0x100
	s_addc_u32 s57, s57, 0
	s_cmp_gt_u32 s58, 13
	s_cbranch_scc0 .LBB0_151
	s_and_b64 vcc, exec, s[40:41]
	s_cbranch_vccz .LBB0_154
	s_barrier

.Ltail_nocs:
	v_and_b32_e32 v5, 63, v227
.LBB0_382:
	v_readfirstlane_b32 s1, v227
	s_lshl_b32 s2, s77, 3
	s_lshl_b32 s33, s78, 3
	s_nop 3
	s_lshr_b32 s0, s1, 6
	s_add_i32 s42, s0, s2
	v_readlane_b32 s4, v253, 56
	v_readlane_b32 s12, v254, 0
	v_readlane_b32 s13, v254, 1
	v_readlane_b32 s14, v254, 2
	v_readlane_b32 s15, v254, 3
	v_readlane_b32 s16, v254, 4
	v_readlane_b32 s17, v254, 5
	v_readlane_b32 s5, v253, 57
	v_readlane_b32 s6, v253, 58
	v_readlane_b32 s7, v253, 59
	v_readlane_b32 s8, v253, 60
	v_readlane_b32 s9, v253, 61
	v_readlane_b32 s18, v254, 6
	v_readlane_b32 s19, v254, 7
	s_mov_b64 s[12:13], s[16:17]
	v_readlane_b32 s10, v253, 62
	v_readlane_b32 s11, v253, 63
	s_mov_b64 s[4:5], s[8:9]
	s_mov_b64 s[14:15], s[18:19]
	v_readfirstlane_b32 s2, v227
	s_mov_b64 s[6:7], s[10:11]
	s_cmpk_gt_i32 s42, 0x14ff
	v_writelane_b32 v253, s0, 56
	s_nop 1
	v_writelane_b32 v253, s1, 57
	v_writelane_b32 v254, s8, 0
	v_writelane_b32 v253, s2, 58
	v_writelane_b32 v254, s9, 1
	v_writelane_b32 v253, s3, 59
	v_writelane_b32 v254, s10, 2
	v_writelane_b32 v253, s4, 60
	v_writelane_b32 v254, s11, 3
	v_writelane_b32 v253, s5, 61
	v_writelane_b32 v254, s12, 4
	v_writelane_b32 v253, s6, 62
	v_writelane_b32 v254, s13, 5
	v_writelane_b32 v253, s7, 63
	v_writelane_b32 v254, s14, 6
	v_writelane_b32 v254, s15, 7
	v_readlane_b32 s4, v253, 8
	v_readlane_b32 s5, v253, 9
	v_readlane_b32 s6, v253, 10
	v_readlane_b32 s7, v253, 11
	v_readlane_b32 s8, v253, 12
	v_readlane_b32 s9, v253, 13
	v_readlane_b32 s10, v253, 14
	v_readlane_b32 s11, v253, 15
	s_nop 0
	v_writelane_b32 v253, s4, 8
	s_nop 1
	v_writelane_b32 v253, s5, 9
	v_writelane_b32 v253, s6, 10
	v_writelane_b32 v253, s7, 11
	v_writelane_b32 v253, s8, 12
	v_writelane_b32 v253, s9, 13
	v_writelane_b32 v253, s10, 14
	v_writelane_b32 v253, s11, 15
	s_nop 0
	v_readlane_b32 s4, v253, 0
	v_readlane_b32 s5, v253, 1
	v_readlane_b32 s6, v253, 2
	v_readlane_b32 s7, v253, 3
	v_readlane_b32 s8, v253, 4
	v_readlane_b32 s9, v253, 5
	v_readlane_b32 s10, v253, 6
	v_readlane_b32 s11, v253, 7
	s_cbranch_scc1 .LBB0_400
	v_lshlrev_b32_e32 v2, 3, v227
	v_and_b32_e32 v18, 56, v2
	s_waitcnt lgkmcnt(0)
	v_mov_b32_e32 v3, 0
	v_lshlrev_b32_e32 v2, 1, v18
	s_add_u32 s6, s8, 0x1537000
	v_lshl_add_u64 v[8:9], s[8:9], 0, v[2:3]
	s_mov_b64 s[0:1], 0x2237000
	s_addc_u32 s7, s9, 0
	v_readlane_b32 s8, v253, 8
	v_lshrrev_b32_e32 v1, 5, v5
	v_lshrrev_b32_e32 v52, 3, v5
	v_lshl_add_u64 v[4:5], v[8:9], 0, s[0:1]
	s_mov_b64 s[0:1], 0x1a37000
	v_readlane_b32 s12, v253, 12
	v_readlane_b32 s13, v253, 13
	v_lshl_add_u64 v[6:7], v[8:9], 0, s[0:1]
	s_mov_b64 s[0:1], 0x1837000
	s_cmp_lg_u64 s[12:13], 0
	v_lshl_add_u64 v[8:9], v[8:9], 0, s[0:1]
	s_cselect_b64 s[0:1], -1, 0
	s_lshr_b32 s2, s2, 6
	v_and_b32_e32 v16, 31, v227
	s_mulk_i32 s2, 0x2100
	v_mul_u32_u24_e32 v17, 0x84, v1
	v_lshlrev_b32_e32 v2, 2, v16
	v_readlane_b32 s10, v253, 10
	v_readlane_b32 s11, v253, 11
	v_readlane_b32 s14, v253, 14
	v_readlane_b32 s15, v253, 15
	s_add_i32 s2, s2, 0
	v_mul_u32_u24_e32 v19, 0x84, v18
	v_lshl_add_u64 v[10:11], s[4:5], 0, v[2:3]
	v_readlane_b32 s9, v253, 9
	v_lshl_add_u64 v[12:13], s[14:15], 0, v[2:3]
	v_lshl_add_u64 v[14:15], s[10:11], 0, v[2:3]
	v_add3_u32 v56, s2, v2, v17
	v_lshlrev_b32_e32 v2, 2, v52
	v_or_b32_e32 v53, 8, v52
	v_or_b32_e32 v54, 16, v52
	v_or_b32_e32 v55, 24, v52
	s_mov_b32 s3, 0
	v_add3_u32 v57, s2, v19, v2
	s_lshl_b32 s8, s42, 2
	s_lshl_b32 s9, s33, 2
	s_lshl_b32 s10, s42, 6
	s_lshl_b32 s11, s33, 6
	s_lshl_b32 s12, s42, 1
	s_lshl_b32 s13, s33, 1
	s_movk_i32 s14, 0x4000
	s_movk_i32 s15, 0x6000
	s_mov_b32 s18, 0x8000
	s_mov_b32 s19, 0xa000
	s_mov_b32 s20, 0xc000
	s_mov_b32 s21, 0xe000
	s_mov_b32 s22, 0x10000
	s_mov_b32 s23, 0x12000
	s_mov_b32 s26, 0x14000
	s_mov_b32 s27, 0x16000
	s_mov_b32 s30, 0x18000
	s_mov_b32 s31, 0x1a000
	s_mov_b32 s34, 0x1c000
	s_mov_b32 s35, 0x1e000
	s_mov_b32 s36, 0x20000
	s_mov_b32 s37, 0x22000
	s_mov_b32 s38, 0x24000
	s_mov_b32 s39, 0x26000
	s_mov_b32 s40, 0x28000
	s_mov_b32 s41, 0x2a000
	s_mov_b32 s43, 0x2c000
	s_mov_b32 s44, 0x2e000
	s_mov_b32 s45, 0x30000
	s_mov_b32 s46, 0x32000
	s_mov_b32 s47, 0x34000
	s_mov_b32 s48, 0x36000
	s_mov_b32 s49, 0x38000
	s_mov_b32 s50, 0x3a000
	s_mov_b32 s51, 0x3c000
	s_mov_b32 s52, 0x3e000
	v_lshlrev_b32_e32 v16, 2, v16
	v_lshlrev_b32_e32 v18, 1, v18
	s_movk_i32 s53, 0x600
	v_add_u32_e32 v58, 0x400, v56
	v_add_u32_e32 v59, 0x800, v56
	v_add_u32_e32 v60, 0xc00, v56
	v_add_u32_e32 v61, 0x1000, v56
	v_add_u32_e32 v62, 0x1400, v56
	v_add_u32_e32 v63, 0x1800, v56
	v_add_u32_e32 v64, 0x1c00, v56
	s_branch .LBB0_385
